# stack2 (flat release, P4 prefetch, paired GDN stores) + P3b CU-partner stagger, on acquire-at-arrival
# speedup vs baseline: 1.0208x; 1.0015x over previous
.LBB0_1031:
	v_cmp_lt_i32_e32 vcc, v21, v22
	v_mov_b32_e32 v0, v181
	s_ashr_i32 s0, s39, 3
	v_cndmask_b32_e32 v2, v20, v21, vcc
	v_cmp_lt_i32_e32 vcc, v23, v22
	s_waitcnt vmcnt(28)
	v_lshlrev_b32_e32 v33, 2, v2
	v_ashrrev_i32_e32 v2, 6, v0
	v_cndmask_b32_e32 v3, v20, v23, vcc
	v_cmp_lt_i32_e32 vcc, v24, v22
	v_lshlrev_b32_e32 v32, 2, v3
	v_and_b32_e32 v3, 63, v0
	v_cndmask_b32_e32 v4, v20, v24, vcc
	v_cmp_lt_i32_e32 vcc, v25, v22
	v_lshlrev_b32_e32 v31, 2, v4
	v_and_b32_e32 v4, 15, v0
	v_cndmask_b32_e32 v5, v20, v25, vcc
	v_lshlrev_b32_e32 v30, 2, v5
	v_lshrrev_b32_e32 v0, 2, v0
	v_lshlrev_b32_e32 v5, 4, v2
	s_lshl_b32 s1, s39, 7
	v_and_b32_e32 v6, 12, v0
	v_lshlrev_b32_e32 v7, 2, v3
	v_lshlrev_b32_e32 v12, 5, v3
	v_lshl_add_u32 v3, s0, 6, v5
	s_and_b32 s4, s39, 0xfffffc00
	s_and_b32 s8, s1, 0x380
	v_lshlrev_b32_e32 v8, 1, v4
	v_lshlrev_b32_e32 v0, 2, v4
	v_or_b32_e32 v5, v5, v4
	v_or_b32_e32 v4, v3, v6
	s_and_b32 s1, s0, 0x7f
	s_or_b32 s4, s8, s4
	global_load_dword v29, v0, s[40:41]
	global_load_dword v28, v0, s[40:41] offset:64
	global_load_dword v27, v0, s[40:41] offset:128
	global_load_dword v26, v0, s[40:41] offset:192
	v_lshlrev_b32_e32 v0, 1, v6
	v_lshlrev_b32_e32 v6, 6, v5
	v_ashrrev_i32_e32 v5, 31, v4
	s_or_b32 s4, s4, s1
	s_waitcnt vmcnt(28)
	v_lshlrev_b64 v[66:67], 13, v[4:5]
	s_ashr_i32 s5, s4, 31
	v_or_b32_e32 v14, 1, v4
	v_or_b32_e32 v16, 2, v4
	v_or_b32_e32 v18, 3, v4
	v_lshl_add_u64 v[4:5], s[20:21], 0, v[66:67]
	s_lshl_b64 s[0:1], s[4:5], 13
	v_lshl_add_u64 v[4:5], v[4:5], 0, s[8:9]
	s_add_u32 s4, s50, s0
	v_lshl_add_u64 v[50:51], v[4:5], 0, v[8:9]
	s_addc_u32 s5, s51, s1
	v_add_co_u32_e32 v52, vcc, s36, v50
	s_add_u32 s6, s17, s0
	s_nop 0
	v_addc_co_u32_e32 v53, vcc, 0, v51, vcc
	v_lshl_or_b32 v2, v2, 10, v7
	v_ashrrev_i32_e32 v7, 31, v6
	s_addc_u32 s7, s29, s1
	v_add_co_u32_e32 v54, vcc, s37, v50
	v_mov_b32_e32 v1, v9
	v_ashrrev_i32_e32 v3, 31, v2
	v_lshl_add_u64 v[6:7], v[6:7], 1, s[4:5]
	s_add_u32 s0, s15, s0
	v_addc_co_u32_e32 v55, vcc, 0, v51, vcc
	v_mov_b32_e32 v13, v9
	v_lshl_add_u64 v[34:35], v[6:7], 0, v[0:1]
	v_lshl_add_u64 v[36:37], v[2:3], 1, s[6:7]
	s_addc_u32 s1, s16, s1
	v_add_co_u32_e32 v56, vcc, s38, v50
	global_load_dwordx2 v[4:5], v[34:35], off
	global_load_dwordx2 v[6:7], v[34:35], off offset:32
	global_load_dwordx2 v[0:1], v[34:35], off offset:64
	global_load_dwordx2 v[2:3], v[34:35], off offset:96
	global_load_dwordx2 v[68:69], v[36:37], off
	global_load_dwordx2 v[72:73], v[36:37], off offset:512
	global_load_dwordx2 v[76:77], v[36:37], off offset:1024
	global_load_dwordx2 v[80:81], v[36:37], off offset:1536
	v_addc_co_u32_e32 v57, vcc, 0, v51, vcc
	global_load_ushort v82, v[50:51], off offset:3072
	global_load_ushort v83, v[50:51], off offset:3104
	global_load_ushort v84, v[50:51], off offset:3136
	global_load_ushort v85, v[50:51], off offset:3168
	global_load_dwordx4 v[34:37], v12, s[0:1]
	global_load_dwordx4 v[38:41], v12, s[0:1] offset:2048
	global_load_dwordx4 v[42:45], v12, s[0:1] offset:16
	global_load_dwordx4 v[46:49], v12, s[0:1] offset:2064
	global_load_ushort v86, v[52:53], off offset:3072
	global_load_ushort v87, v[54:55], off offset:3072
	global_load_ushort v88, v[56:57], off offset:3072
	global_load_ushort v89, v[52:53], off offset:3104
	global_load_ushort v90, v[54:55], off offset:3104
	global_load_ushort v91, v[56:57], off offset:3104
	global_load_ushort v92, v[52:53], off offset:3136
	global_load_ushort v93, v[54:55], off offset:3136
	global_load_ushort v94, v[56:57], off offset:3136
	global_load_ushort v95, v[54:55], off offset:3168
	global_load_ushort v96, v[52:53], off offset:3168
	global_load_ushort v97, v[56:57], off offset:3168
	v_lshl_add_u64 v[12:13], s[0:1], 0, v[12:13]
	v_lshl_add_u64 v[70:71], v[12:13], 0, s[10:11]
	s_waitcnt vmcnt(55)
	v_lshl_add_u64 v[74:75], v[12:13], 0, s[12:13]
	v_add_co_u32_e32 v12, vcc, s34, v12
	s_add_u32 s0, s20, s8
	s_nop 0
	v_addc_co_u32_e32 v13, vcc, 0, v13, vcc
	global_load_dwordx4 v[50:53], v[12:13], off
	global_load_dwordx4 v[54:57], v[12:13], off offset:2048
	global_load_dwordx4 v[58:61], v[70:71], off offset:16
	global_load_dwordx4 v[62:65], v[74:75], off offset:16
	s_addc_u32 s1, s21, 0
	v_and_b32_e32 v12, 0xffe00000, v66
	v_lshrrev_b32_e32 v13, 5, v66
	v_and_b32_e32 v13, 0xe000, v13
	v_lshrrev_b32_e32 v14, 7, v66
	v_and_b32_e32 v14, 0x7c0, v14
	v_lshrrev_b32_e32 v15, 10, v66
	v_and_b32_e32 v15, 32, v15
	v_and_b32_e32 v16, 30, v8
	v_or3_b32 v12, v12, v13, v14
	v_or3_b32 v12, v12, v15, v16
	s_lshl_b32 s8, s8, 10
	v_add_u32_e32 v12, s8, v12
	v_xor_b32_e32 v16, 16, v12
	v_add_u32_e32 v14, 64, v12
	v_add_u32_e32 v18, 0xc0, v16
	v_add_u32_e32 v16, 0x80, v16
	v_xor_b32_e32 v13, 32, v12
	v_xor_b32_e32 v15, 32, v14
	v_xor_b32_e32 v17, 32, v16
	v_xor_b32_e32 v19, 32, v18
	v_add_u32_e32 v14, -2, v14
	v_add_u32_e32 v15, -2, v15
	v_add_u32_e32 v18, -2, v18
	v_add_u32_e32 v19, -2, v19
	v_cndmask_b32_e64 v12, v14, v12, s[72:73]
	v_cndmask_b32_e64 v13, v15, v13, s[72:73]
	v_cndmask_b32_e64 v16, v18, v16, s[72:73]
	v_cndmask_b32_e64 v17, v19, v17, s[72:73]
	s_add_i32 s39, s39, s22
	s_cmpk_lt_i32 s39, 0x1000
	s_waitcnt vmcnt(23)
	v_lshlrev_b32_e32 v8, 16, v82
	s_waitcnt vmcnt(22)
	v_lshlrev_b32_e32 v98, 16, v83
	s_waitcnt vmcnt(21)
	v_lshlrev_b32_e32 v99, 16, v84
	s_waitcnt vmcnt(20)
	v_lshlrev_b32_e32 v100, 16, v85
	s_waitcnt vmcnt(19)
	v_mov_b32_e32 v82, v34
	v_mov_b32_e32 v83, v35
	s_waitcnt vmcnt(18)
	v_mov_b32_e32 v84, v38
	v_mov_b32_e32 v85, v39
	s_waitcnt vmcnt(17)
	v_mov_b32_e32 v34, v42
	v_mov_b32_e32 v35, v43
	v_mul_f32_e32 v42, 0xbfb8aa3b, v8
	v_mul_f32_e32 v43, 0xbfb8aa3b, v98
	v_mov_b32_e32 v38, v36
	v_mov_b32_e32 v39, v37
	v_lshlrev_b32_e32 v66, 16, v68
	v_and_b32_e32 v67, 0xffff0000, v68
	v_lshlrev_b32_e32 v68, 16, v69
	v_and_b32_e32 v69, 0xffff0000, v69
	v_lshlrev_b32_e32 v70, 16, v72
	v_and_b32_e32 v71, 0xffff0000, v72
	v_lshlrev_b32_e32 v72, 16, v73
	v_and_b32_e32 v73, 0xffff0000, v73
	s_waitcnt vmcnt(16)
	v_mov_b32_e32 v36, v46
	v_mov_b32_e32 v37, v47
	v_mov_b32_e32 v46, v44
	v_mov_b32_e32 v47, v45
	v_exp_f32_e32 v103, v42
	v_exp_f32_e32 v107, v43
	v_mfma_f32_16x16x32_bf16 v[42:45], v[4:7], v[82:85], v[66:69]
	v_lshlrev_b32_e32 v74, 16, v76
	v_and_b32_e32 v75, 0xffff0000, v76
	v_lshlrev_b32_e32 v76, 16, v77
	v_and_b32_e32 v77, 0xffff0000, v77
	v_lshlrev_b32_e32 v78, 16, v80
	v_and_b32_e32 v79, 0xffff0000, v80
	v_lshlrev_b32_e32 v80, 16, v81
	v_and_b32_e32 v81, 0xffff0000, v81
	s_waitcnt vmcnt(15)
	v_lshlrev_b32_e32 v86, 16, v86
	s_waitcnt vmcnt(14)
	v_lshlrev_b32_e32 v87, 16, v87
	v_mul_f32_e32 v101, 0xbfb8aa3b, v99
	v_mfma_f32_16x16x32_bf16 v[38:41], v[4:7], v[38:41], v[70:73]
	s_waitcnt vmcnt(8)
	v_lshlrev_b32_e32 v93, 16, v93
	s_waitcnt vmcnt(7)
	v_lshlrev_b32_e32 v94, 16, v94
	v_mul_f32_e32 v104, 0xbfb8aa3b, v86
	v_mul_f32_e32 v105, 0xbfb8aa3b, v87
	v_exp_f32_e32 v67, v101
	v_mfma_f32_16x16x32_bf16 v[34:37], v[4:7], v[34:37], v[74:77]
	v_lshlrev_b32_e32 v88, 16, v88
	v_lshlrev_b32_e32 v89, 16, v89
	v_lshlrev_b32_e32 v90, 16, v90
	v_mfma_f32_16x16x32_bf16 v[4:7], v[4:7], v[46:49], v[78:81]
	v_lshlrev_b32_e32 v92, 16, v92
	s_waitcnt vmcnt(5)
	v_lshlrev_b32_e32 v96, 16, v96
	v_lshlrev_b32_e32 v95, 16, v95
	v_mul_f32_e32 v69, 0xbfb8aa3b, v93
	v_mul_f32_e32 v70, 0xbfb8aa3b, v94
	s_waitcnt vmcnt(3)
	v_mov_b32_e32 v46, v50
	v_mov_b32_e32 v47, v51
	s_waitcnt vmcnt(2)
	v_mov_b32_e32 v48, v54
	v_mov_b32_e32 v49, v55
	s_waitcnt vmcnt(1)
	v_mov_b32_e32 v50, v58
	v_mov_b32_e32 v51, v59
	v_exp_f32_e32 v58, v104
	v_exp_f32_e32 v59, v105
	v_lshlrev_b32_e32 v91, 16, v91
	v_mul_f32_e32 v102, 0xbfb8aa3b, v100
	v_lshlrev_b32_e32 v97, 16, v97
	v_mul_f32_e32 v106, 0xbfb8aa3b, v88
	v_mul_f32_e32 v108, 0xbfb8aa3b, v89
	v_mul_f32_e32 v109, 0xbfb8aa3b, v90
	v_mul_f32_e32 v68, 0xbfb8aa3b, v92
	v_mul_f32_e32 v72, 0xbfb8aa3b, v96
	v_mul_f32_e32 v73, 0xbfb8aa3b, v95
	v_mov_b32_e32 v54, v52
	v_mov_b32_e32 v55, v53
	v_mfma_f32_16x16x32_bf16 v[42:45], v[0:3], v[46:49], v[42:45]
	v_exp_f32_e32 v46, v69
	v_exp_f32_e32 v47, v70
	v_mul_f32_e32 v66, 0xbfb8aa3b, v91
	v_exp_f32_e32 v71, v102
	v_mul_f32_e32 v74, 0xbfb8aa3b, v97
	s_waitcnt vmcnt(0)
	v_mov_b32_e32 v52, v62
	v_mov_b32_e32 v53, v63
	v_mov_b32_e32 v62, v60
	v_mov_b32_e32 v63, v61
	v_exp_f32_e32 v60, v106
	v_exp_f32_e32 v61, v108
	v_exp_f32_e32 v75, v109
	v_exp_f32_e32 v68, v68
	v_exp_f32_e32 v48, v72
	v_mfma_f32_16x16x32_bf16 v[38:41], v[0:3], v[54:57], v[38:41]
	v_exp_f32_e32 v49, v73
	v_exp_f32_e32 v66, v66
	v_exp_f32_e32 v54, v74
	v_add_f32_e32 v55, 1.0, v103
	v_mfma_f32_16x16x32_bf16 v[34:37], v[0:3], v[50:53], v[34:37]
	v_add_f32_e32 v50, 1.0, v107
	v_add_f32_e32 v51, 1.0, v67
	v_add_f32_e32 v46, 1.0, v46
	v_mfma_f32_16x16x32_bf16 v[0:3], v[0:3], v[62:65], v[4:7]
	v_rcp_f32_e32 v62, v55
	v_add_f32_e32 v47, 1.0, v47
	v_add_f32_e32 v52, 1.0, v71
	v_add_f32_e32 v4, 1.0, v58
	v_add_f32_e32 v5, 1.0, v59
	v_rcp_f32_e32 v58, v50
	v_rcp_f32_e32 v59, v51
	v_add_f32_e32 v6, 1.0, v60
	v_add_f32_e32 v7, 1.0, v61
	v_add_f32_e32 v50, 1.0, v75
	v_add_f32_e32 v51, 1.0, v68
	v_add_f32_e32 v48, 1.0, v48
	v_add_f32_e32 v49, 1.0, v49
	v_rcp_f32_e32 v61, v4
	v_rcp_f32_e32 v63, v5
	v_rcp_f32_e32 v69, v46
	v_rcp_f32_e32 v70, v47
	v_mov_b32_e32 v4, v42
	v_mov_b32_e32 v5, v38
	v_mov_b32_e32 v46, v43
	v_mov_b32_e32 v47, v39
	v_add_f32_e32 v53, 1.0, v66
	v_rcp_f32_e32 v60, v52
	v_add_f32_e32 v52, 1.0, v54
	v_rcp_f32_e32 v64, v6
	v_rcp_f32_e32 v65, v7
	v_rcp_f32_e32 v66, v50
	v_rcp_f32_e32 v68, v51
	v_rcp_f32_e32 v71, v48
	v_rcp_f32_e32 v72, v49
	v_mov_b32_e32 v6, v34
	v_mov_b32_e32 v7, v0
	v_mov_b32_e32 v48, v35
	v_mov_b32_e32 v49, v1
	v_mov_b32_e32 v50, v44
	v_mov_b32_e32 v51, v40
	v_mov_b32_e32 v54, v45
	v_mov_b32_e32 v55, v41
	v_pk_mul_f32 v[4:5], v[4:5], v[4:5]
	v_pk_mul_f32 v[46:47], v[46:47], v[46:47]
	v_rcp_f32_e32 v67, v53
	v_rcp_f32_e32 v73, v52
	v_mov_b32_e32 v52, v36
	v_mov_b32_e32 v53, v2
	v_mov_b32_e32 v56, v37
	v_mov_b32_e32 v57, v3
	v_mul_f32_e32 v8, v62, v8
	v_mul_f32_e32 v62, v58, v98
	v_mul_f32_e32 v74, v59, v99
	v_pk_mul_f32 v[6:7], v[6:7], v[6:7]
	v_pk_mul_f32 v[48:49], v[48:49], v[48:49]
	v_pk_mul_f32 v[50:51], v[50:51], v[50:51]
	v_pk_mul_f32 v[54:55], v[54:55], v[54:55]
	v_mov_b32_e32 v58, v46
	v_mov_b32_e32 v59, v4
	v_mov_b32_e32 v4, v47
	v_pk_mul_f32 v[52:53], v[52:53], v[52:53]
	v_pk_mul_f32 v[56:57], v[56:57], v[56:57]
	v_mov_b32_e32 v46, v48
	v_mov_b32_e32 v47, v6
	v_mov_b32_e32 v6, v49
	v_mov_b32_e32 v48, v54
	v_mov_b32_e32 v49, v50
	v_mov_b32_e32 v50, v55
	v_pk_add_f32 v[4:5], v[58:59], v[4:5]
	v_mov_b32_e32 v54, v56
	v_mov_b32_e32 v55, v52
	v_pk_add_f32 v[48:49], v[48:49], v[50:51]
	v_pk_add_f32 v[4:5], v[4:5], v[46:47]
	v_mov_b32_e32 v52, v57
	v_pk_add_f32 v[46:47], v[48:49], v[54:55]
	v_pk_add_f32 v[4:5], v[4:5], v[6:7]
	v_pk_add_f32 v[6:7], v[46:47], v[52:53]
	ds_bpermute_b32 v47, v33, v5
	ds_bpermute_b32 v46, v33, v4
	ds_bpermute_b32 v49, v33, v7
	ds_bpermute_b32 v48, v33, v6
	v_mul_f32_e32 v60, v60, v100
	v_mul_f32_e32 v61, v61, v86
	s_waitcnt lgkmcnt(2)
	v_pk_add_f32 v[4:5], v[4:5], v[46:47]
	ds_bpermute_b32 v47, v32, v5
	s_waitcnt lgkmcnt(1)
	v_pk_add_f32 v[6:7], v[6:7], v[48:49]
	ds_bpermute_b32 v46, v32, v4
	ds_bpermute_b32 v33, v32, v7
	ds_bpermute_b32 v32, v32, v6
	v_mul_f32_e32 v63, v63, v87
	v_mul_f32_e32 v64, v64, v88
	s_waitcnt lgkmcnt(2)
	v_pk_add_f32 v[4:5], v[4:5], v[46:47]
	v_mul_f32_e32 v65, v65, v89
	s_waitcnt lgkmcnt(0)
	v_pk_add_f32 v[6:7], v[6:7], v[32:33]
	ds_bpermute_b32 v33, v31, v5
	ds_bpermute_b32 v32, v31, v4
	ds_bpermute_b32 v47, v31, v7
	ds_bpermute_b32 v46, v31, v6
	v_mul_f32_e32 v66, v66, v90
	v_mul_f32_e32 v67, v67, v91
	s_waitcnt lgkmcnt(2)
	v_pk_add_f32 v[4:5], v[4:5], v[32:33]
	ds_bpermute_b32 v33, v30, v5
	s_waitcnt lgkmcnt(1)
	v_pk_add_f32 v[6:7], v[6:7], v[46:47]
	ds_bpermute_b32 v32, v30, v4
	ds_bpermute_b32 v31, v30, v7
	ds_bpermute_b32 v30, v30, v6
	v_mul_f32_e32 v68, v68, v92
	v_mul_f32_e32 v69, v69, v93
	s_waitcnt lgkmcnt(2)
	v_pk_add_f32 v[4:5], v[4:5], v[32:33]
	v_mul_f32_e32 v70, v70, v94
	s_waitcnt lgkmcnt(0)
	v_pk_add_f32 v[6:7], v[6:7], v[30:31]
	v_pk_fma_f32 v[4:5], v[4:5], s[14:15], v[10:11] op_sel_hi:[1,0,0]
	v_pk_fma_f32 v[6:7], v[6:7], s[14:15], v[10:11] op_sel_hi:[1,0,0]
	v_mul_f32_e32 v30, 0x4b800000, v5
	v_cmp_gt_f32_e64 s[6:7], s35, v5
	v_mul_f32_e32 v31, 0x4b800000, v4
	v_cmp_gt_f32_e32 vcc, s35, v4
	v_mul_f32_e32 v32, 0x4b800000, v7
	v_mul_f32_e32 v33, 0x4b800000, v6
	v_cmp_gt_f32_e64 s[0:1], s35, v6
	v_cmp_gt_f32_e64 s[4:5], s35, v7
	v_cndmask_b32_e64 v5, v5, v30, s[6:7]
	v_cndmask_b32_e32 v4, v4, v31, vcc
	v_cndmask_b32_e64 v7, v7, v32, s[4:5]
	v_cndmask_b32_e64 v6, v6, v33, s[0:1]
	v_rsq_f32_e32 v5, v5
	v_rsq_f32_e32 v4, v4
	v_rsq_f32_e32 v7, v7
	v_rsq_f32_e32 v6, v6
	v_mul_f32_e32 v30, 0x45800000, v5
	v_mul_f32_e32 v31, 0x45800000, v4
	v_mul_f32_e32 v32, 0x45800000, v7
	v_mul_f32_e32 v33, 0x45800000, v6
	v_cndmask_b32_e64 v5, v5, v30, s[6:7]
	v_cndmask_b32_e32 v4, v4, v31, vcc
	v_cndmask_b32_e64 v7, v7, v32, s[4:5]
	v_cndmask_b32_e64 v6, v6, v33, s[0:1]
	v_mul_f32_e32 v30, v42, v5
	v_mul_f32_e32 v31, v43, v4
	v_mul_f32_e32 v32, v44, v7
	v_mul_f32_e32 v33, v45, v6
	v_mul_f32_e32 v38, v38, v5
	v_mul_f32_e32 v39, v39, v4
	v_mul_f32_e32 v40, v40, v7
	v_mul_f32_e32 v41, v41, v6
	v_mul_f32_e32 v34, v34, v5
	v_mul_f32_e32 v35, v35, v4
	v_mul_f32_e32 v36, v36, v7
	v_mul_f32_e32 v37, v37, v6
	v_mul_f32_e32 v0, v0, v5
	v_mul_f32_e32 v1, v1, v4
	v_mul_f32_e32 v2, v2, v7
	v_mul_f32_e32 v3, v3, v6
	v_mul_f32_e32 v4, v29, v30
	v_mul_f32_e32 v71, v71, v96
	v_mul_f32_e32 v72, v72, v95
	v_mul_f32_e32 v73, v73, v97
	v_mul_f32_e32 v5, v29, v31
	v_mul_f32_e32 v6, v29, v32
	v_mul_f32_e32 v7, v29, v33
	v_mul_f32_e32 v29, v28, v38
	v_mul_f32_e32 v30, v28, v39
	v_mul_f32_e32 v31, v28, v40
	v_mul_f32_e32 v28, v28, v41
	v_mul_f32_e32 v32, v27, v34
	v_mul_f32_e32 v33, v27, v35
	v_mul_f32_e32 v34, v27, v36
	v_mul_f32_e32 v27, v27, v37
	v_mul_f32_e32 v0, v26, v0
	v_mul_f32_e32 v1, v26, v1
	v_mul_f32_e32 v2, v26, v2
	v_mul_f32_e32 v3, v26, v3
	v_mul_f32_e32 v4, v8, v4
	v_mul_f32_e32 v5, v61, v5
	v_mul_f32_e32 v6, v63, v6
	v_mul_f32_e32 v7, v64, v7
	v_mul_f32_e32 v8, v62, v29
	v_mul_f32_e32 v26, v65, v30
	v_mul_f32_e32 v29, v66, v31
	v_mul_f32_e32 v28, v67, v28
	v_mul_f32_e32 v30, v74, v32
	v_mul_f32_e32 v31, v68, v33
	v_mul_f32_e32 v32, v69, v34
	v_mul_f32_e32 v27, v70, v27
	v_mul_f32_e32 v0, v60, v0
	v_mul_f32_e32 v1, v71, v1
	v_mul_f32_e32 v2, v72, v2
	v_mul_f32_e32 v3, v73, v3
	v_cndmask_b32_e64 v40, v5, v4, s[72:73]
	v_cndmask_b32_e64 v48, v4, v5, s[72:73]
	v_cndmask_b32_e64 v41, v7, v6, s[72:73]
	v_cndmask_b32_e64 v49, v6, v7, s[72:73]
	v_cndmask_b32_e64 v42, v26, v8, s[72:73]
	v_cndmask_b32_e64 v50, v8, v26, s[72:73]
	v_cndmask_b32_e64 v43, v28, v29, s[72:73]
	v_cndmask_b32_e64 v51, v29, v28, s[72:73]
	v_cndmask_b32_e64 v44, v31, v30, s[72:73]
	v_cndmask_b32_e64 v52, v30, v31, s[72:73]
	v_cndmask_b32_e64 v45, v27, v32, s[72:73]
	v_cndmask_b32_e64 v53, v32, v27, s[72:73]
	v_cndmask_b32_e64 v46, v1, v0, s[72:73]
	v_cndmask_b32_e64 v54, v0, v1, s[72:73]
	v_cndmask_b32_e64 v47, v3, v2, s[72:73]
	v_cndmask_b32_e64 v55, v2, v3, s[72:73]
	v_mov_b32_dpp v56, v48 quad_perm:[1,0,3,2] row_mask:0xf bank_mask:0xf
	v_mov_b32_dpp v57, v49 quad_perm:[1,0,3,2] row_mask:0xf bank_mask:0xf
	v_mov_b32_dpp v58, v50 quad_perm:[1,0,3,2] row_mask:0xf bank_mask:0xf
	v_mov_b32_dpp v59, v51 quad_perm:[1,0,3,2] row_mask:0xf bank_mask:0xf
	v_mov_b32_dpp v60, v52 quad_perm:[1,0,3,2] row_mask:0xf bank_mask:0xf
	v_mov_b32_dpp v61, v53 quad_perm:[1,0,3,2] row_mask:0xf bank_mask:0xf
	v_mov_b32_dpp v62, v54 quad_perm:[1,0,3,2] row_mask:0xf bank_mask:0xf
	v_mov_b32_dpp v63, v55 quad_perm:[1,0,3,2] row_mask:0xf bank_mask:0xf
	v_cndmask_b32_e64 v48, v56, v40, s[72:73]
	v_cndmask_b32_e64 v56, v40, v56, s[72:73]
	v_cndmask_b32_e64 v49, v57, v41, s[72:73]
	v_cndmask_b32_e64 v57, v41, v57, s[72:73]
	v_cndmask_b32_e64 v50, v58, v42, s[72:73]
	v_cndmask_b32_e64 v58, v42, v58, s[72:73]
	v_cndmask_b32_e64 v51, v59, v43, s[72:73]
	v_cndmask_b32_e64 v59, v43, v59, s[72:73]
	v_cndmask_b32_e64 v52, v60, v44, s[72:73]
	v_cndmask_b32_e64 v60, v44, v60, s[72:73]
	v_cndmask_b32_e64 v53, v61, v45, s[72:73]
	v_cndmask_b32_e64 v61, v45, v61, s[72:73]
	v_cndmask_b32_e64 v54, v62, v46, s[72:73]
	v_cndmask_b32_e64 v62, v46, v62, s[72:73]
	v_cndmask_b32_e64 v55, v63, v47, s[72:73]
	v_cndmask_b32_e64 v63, v47, v63, s[72:73]
	v_cvt_pk_bf16_f32 v40, v48, v56
	v_cvt_pk_bf16_f32 v41, v49, v57
	v_cvt_pk_bf16_f32 v42, v50, v58
	v_cvt_pk_bf16_f32 v43, v51, v59
	v_cvt_pk_bf16_f32 v44, v52, v60
	v_cvt_pk_bf16_f32 v45, v53, v61
	v_cvt_pk_bf16_f32 v46, v54, v62
	v_cvt_pk_bf16_f32 v47, v55, v63
	global_store_dword v12, v40, s[20:21]
	global_store_dword v16, v41, s[20:21]
	global_store_dword v13, v42, s[20:21]
	global_store_dword v17, v43, s[20:21]
	global_store_dword v12, v44, s[100:101]
	global_store_dword v16, v45, s[100:101]
	global_store_dword v13, v46, s[100:101]
	global_store_dword v17, v47, s[100:101]
	s_cbranch_scc1 .LBB0_1031
	s_cmp_eq_u32 s96, 1
	s_cbranch_scc0 .LBB0_1032
	s_mov_b32 s96, 2
	s_branch .Lp3b_scan
